# v24
# speedup vs baseline: 1.0035x; 1.0035x over previous
; __device__ __forceinline__ unsigned xb_ld(unsigned* p)              { return __hip_atomic_load(p, __ATOMIC_RELAXED, __HIP_MEMORY_SCOPE_AGENT); }
; __device__ __forceinline__ unsigned xb_add(unsigned* p, unsigned v) { return __hip_atomic_fetch_add(p, v, __ATOMIC_RELAXED, __HIP_MEMORY_SCOPE_AGENT); }
; #define XB_SPIN(cond, bar) do { unsigned _sp = 0; while (cond) { \
;     if ((++_sp & 255u) == 0u) { if (xb_ld(&(bar)[XB_TMO])) break; if (_sp > XB_SPIN_CAP) { atomicAdd(&(bar)[XB_TMO], 1u); break; } } } } while (0)
; __device__ __forceinline__ void xcd_barrier(const XcdBarrier& b) {
;     ...
;         unsigned nloc = b.st[0], nx = b.st[1];
;         if (nloc == 0u) { xcd_barrier_complete(bar, b.x, nloc, nx); b.st[0] = nloc; b.st[1] = nx; }
;         const unsigned old = xb_add(&bar[XB_XSUB(b.x)], 1u);
;         const unsigned gen = old / nloc;
;         if (old + 1u == (gen + 1u) * nloc) {
;             __builtin_amdgcn_fence(__ATOMIC_RELEASE, "agent");
;             asm volatile("s_waitcnt vmcnt(0)" ::: "memory");
;             const unsigned og = xb_add(&bar[XB_TOP], 1u);
;             const unsigned tg = og / nx;
;             if (og + 1u == (tg + 1u) * nx) xb_add(&bar[XB_TOPGEN], 1u);
;             else XB_SPIN(xb_ld(&bar[XB_TOPGEN]) == tg, bar);
;             xb_add(&bar[XB_XGEN(b.x)], 1u);
;             __builtin_amdgcn_fence(__ATOMIC_ACQUIRE, "agent");
;             asm volatile("s_waitcnt vmcnt(0)" ::: "memory");
;         } else {
;             XB_SPIN(xb_ld(&bar[XB_XGEN(b.x)]) == gen, bar);
.LBB0_61:
	s_or_b64 exec, exec, s[16:17]
	v_cvt_f32_u32_e32 v4, v2
	s_waitcnt vmcnt(0)
	v_readfirstlane_b32 s3, v3
	v_sub_u32_e32 v3, 0, v2
	v_rcp_iflag_f32_e32 v4, v4
	v_add_u32_e32 v5, s3, v1
	v_mul_f32_e32 v4, 0x4f7ffffe, v4
	v_cvt_u32_f32_e32 v4, v4
	v_mul_lo_u32 v1, v3, v4
	v_mul_hi_u32 v1, v4, v1
	v_add_u32_e32 v1, v4, v1
	v_mul_hi_u32 v1, v5, v1
	v_mul_lo_u32 v3, v1, v2
	v_sub_u32_e32 v3, v5, v3
	v_add_u32_e32 v4, 1, v1
	v_cmp_ge_u32_e32 vcc, v3, v2
	s_nop 1
	v_cndmask_b32_e32 v1, v1, v4, vcc
	v_sub_u32_e32 v4, v3, v2
	v_cndmask_b32_e32 v3, v3, v4, vcc
	v_add_u32_e32 v4, 1, v1
	v_cmp_ge_u32_e32 vcc, v3, v2
	v_add_u32_e32 v3, 1, v5
	s_nop 0
	v_cndmask_b32_e32 v1, v1, v4, vcc
	v_mul_lo_u32 v4, v2, v1
	v_add_u32_e32 v2, v4, v2
	v_cmp_ne_u32_e32 vcc, v3, v2
	s_and_saveexec_b64 s[8:9], vcc
	s_xor_b64 s[14:15], exec, s[8:9]
	s_cbranch_execz .LBB0_75
	v_cmp_eq_u32_e32 vcc, v5, v4
	s_cbranch_vccz .Lxb_nofirst_0
	buffer_wbl2 sc1
.Lxb_nofirst_0:
	s_waitcnt lgkmcnt(0)
	v_mov_b32_e32 v0, 0x2000
	global_load_dword v0, v0, s[10:11] offset:1024 sc1
	s_add_u32 s18, s10, 0x2400
	s_addc_u32 s19, s11, 0
	s_waitcnt vmcnt(0)
	v_cmp_eq_u32_e32 vcc, v0, v1
	s_and_saveexec_b64 s[16:17], vcc
	s_cbranch_execz .LBB0_74
	s_mov_b32 s3, 1
	s_mov_b64 s[20:21], 0
	v_mov_b32_e32 v0, 0
	s_branch .LBB0_65

; __device__ __forceinline__ unsigned xb_ld(unsigned* p)              { return __hip_atomic_load(p, __ATOMIC_RELAXED, __HIP_MEMORY_SCOPE_AGENT); }
; __device__ __forceinline__ unsigned xb_add(unsigned* p, unsigned v) { return __hip_atomic_fetch_add(p, v, __ATOMIC_RELAXED, __HIP_MEMORY_SCOPE_AGENT); }
; #define XB_SPIN(cond, bar) do { unsigned _sp = 0; while (cond) { \
;     if ((++_sp & 255u) == 0u) { if (xb_ld(&(bar)[XB_TMO])) break; if (_sp > XB_SPIN_CAP) { atomicAdd(&(bar)[XB_TMO], 1u); break; } } } } while (0)
; __device__ __forceinline__ void xcd_barrier(const XcdBarrier& b) {
;     ...
;         unsigned nloc = b.st[0], nx = b.st[1];
;         if (nloc == 0u) { xcd_barrier_complete(bar, b.x, nloc, nx); b.st[0] = nloc; b.st[1] = nx; }
;         const unsigned old = xb_add(&bar[XB_XSUB(b.x)], 1u);
;         const unsigned gen = old / nloc;
;         if (old + 1u == (gen + 1u) * nloc) {
;             __builtin_amdgcn_fence(__ATOMIC_RELEASE, "agent");
;             asm volatile("s_waitcnt vmcnt(0)" ::: "memory");
;             const unsigned og = xb_add(&bar[XB_TOP], 1u);
;             const unsigned tg = og / nx;
;             if (og + 1u == (tg + 1u) * nx) xb_add(&bar[XB_TOPGEN], 1u);
;             else XB_SPIN(xb_ld(&bar[XB_TOPGEN]) == tg, bar);
;             xb_add(&bar[XB_XGEN(b.x)], 1u);
;             __builtin_amdgcn_fence(__ATOMIC_ACQUIRE, "agent");
;             asm volatile("s_waitcnt vmcnt(0)" ::: "memory");
;         } else {
;             XB_SPIN(xb_ld(&bar[XB_XGEN(b.x)]) == gen, bar);
.LBB0_354:
	s_or_b64 exec, exec, s[14:15]
	v_cvt_f32_u32_e32 v4, v2
	s_waitcnt vmcnt(0)
	v_readfirstlane_b32 s3, v3
	v_sub_u32_e32 v3, 0, v2
	v_rcp_iflag_f32_e32 v4, v4
	v_add_u32_e32 v5, s3, v1
	v_mul_f32_e32 v4, 0x4f7ffffe, v4
	v_cvt_u32_f32_e32 v4, v4
	v_mul_lo_u32 v1, v3, v4
	v_mul_hi_u32 v1, v4, v1
	v_add_u32_e32 v1, v4, v1
	v_mul_hi_u32 v1, v5, v1
	v_mul_lo_u32 v3, v1, v2
	v_sub_u32_e32 v3, v5, v3
	v_add_u32_e32 v4, 1, v1
	v_cmp_ge_u32_e32 vcc, v3, v2
	s_nop 1
	v_cndmask_b32_e32 v1, v1, v4, vcc
	v_sub_u32_e32 v4, v3, v2
	v_cndmask_b32_e32 v3, v3, v4, vcc
	v_add_u32_e32 v4, 1, v1
	v_cmp_ge_u32_e32 vcc, v3, v2
	v_add_u32_e32 v3, 1, v5
	s_nop 0
	v_cndmask_b32_e32 v1, v1, v4, vcc
	v_mul_lo_u32 v4, v2, v1
	v_add_u32_e32 v2, v4, v2
	v_cmp_ne_u32_e32 vcc, v3, v2
	s_and_saveexec_b64 s[8:9], vcc
	s_xor_b64 s[10:11], exec, s[8:9]
	s_cbranch_execz .LBB0_368
	v_cmp_eq_u32_e32 vcc, v5, v4
	s_cbranch_vccz .Lxb_nofirst_2
	buffer_wbl2 sc1
.Lxb_nofirst_2:
	s_waitcnt lgkmcnt(0)
	v_mov_b32_e32 v0, 0x2000
	global_load_dword v0, v0, s[6:7] offset:1024 sc1
	s_add_u32 s16, s6, 0x2400
	s_addc_u32 s17, s7, 0
	s_waitcnt vmcnt(0)
	v_cmp_eq_u32_e32 vcc, v0, v1
	s_and_saveexec_b64 s[14:15], vcc
	s_cbranch_execz .LBB0_367
	s_mov_b32 s3, 1
	s_mov_b64 s[18:19], 0
	v_mov_b32_e32 v0, 0
	s_branch .LBB0_358

; __device__ __forceinline__ unsigned xb_ld(unsigned* p)              { return __hip_atomic_load(p, __ATOMIC_RELAXED, __HIP_MEMORY_SCOPE_AGENT); }
; __device__ __forceinline__ unsigned xb_add(unsigned* p, unsigned v) { return __hip_atomic_fetch_add(p, v, __ATOMIC_RELAXED, __HIP_MEMORY_SCOPE_AGENT); }
; #define XB_SPIN(cond, bar) do { unsigned _sp = 0; while (cond) { \
;     if ((++_sp & 255u) == 0u) { if (xb_ld(&(bar)[XB_TMO])) break; if (_sp > XB_SPIN_CAP) { atomicAdd(&(bar)[XB_TMO], 1u); break; } } } } while (0)
; __device__ __forceinline__ void xcd_barrier(const XcdBarrier& b) {
;     ...
;         unsigned nloc = b.st[0], nx = b.st[1];
;         if (nloc == 0u) { xcd_barrier_complete(bar, b.x, nloc, nx); b.st[0] = nloc; b.st[1] = nx; }
;         const unsigned old = xb_add(&bar[XB_XSUB(b.x)], 1u);
;         const unsigned gen = old / nloc;
;         if (old + 1u == (gen + 1u) * nloc) {
;             __builtin_amdgcn_fence(__ATOMIC_RELEASE, "agent");
;             asm volatile("s_waitcnt vmcnt(0)" ::: "memory");
;             const unsigned og = xb_add(&bar[XB_TOP], 1u);
;             const unsigned tg = og / nx;
;             if (og + 1u == (tg + 1u) * nx) xb_add(&bar[XB_TOPGEN], 1u);
;             else XB_SPIN(xb_ld(&bar[XB_TOPGEN]) == tg, bar);
;             xb_add(&bar[XB_XGEN(b.x)], 1u);
;             __builtin_amdgcn_fence(__ATOMIC_ACQUIRE, "agent");
;             asm volatile("s_waitcnt vmcnt(0)" ::: "memory");
;         } else {
;             XB_SPIN(xb_ld(&bar[XB_XGEN(b.x)]) == gen, bar);
.LBB0_731:
	s_or_b64 exec, exec, s[14:15]
	v_cvt_f32_u32_e32 v4, v2
	s_waitcnt vmcnt(0)
	v_readfirstlane_b32 s3, v3
	v_sub_u32_e32 v3, 0, v2
	v_rcp_iflag_f32_e32 v4, v4
	v_add_u32_e32 v5, s3, v1
	v_mul_f32_e32 v4, 0x4f7ffffe, v4
	v_cvt_u32_f32_e32 v4, v4
	v_mul_lo_u32 v1, v3, v4
	v_mul_hi_u32 v1, v4, v1
	v_add_u32_e32 v1, v4, v1
	v_mul_hi_u32 v1, v5, v1
	v_mul_lo_u32 v3, v1, v2
	v_sub_u32_e32 v3, v5, v3
	v_add_u32_e32 v4, 1, v1
	v_cmp_ge_u32_e32 vcc, v3, v2
	s_nop 1
	v_cndmask_b32_e32 v1, v1, v4, vcc
	v_sub_u32_e32 v4, v3, v2
	v_cndmask_b32_e32 v3, v3, v4, vcc
	v_add_u32_e32 v4, 1, v1
	v_cmp_ge_u32_e32 vcc, v3, v2
	v_add_u32_e32 v3, 1, v5
	s_nop 0
	v_cndmask_b32_e32 v1, v1, v4, vcc
	v_mul_lo_u32 v4, v2, v1
	v_add_u32_e32 v2, v4, v2
	v_cmp_ne_u32_e32 vcc, v3, v2
	s_and_saveexec_b64 s[8:9], vcc
	s_xor_b64 s[12:13], exec, s[8:9]
	s_cbranch_execz .LBB0_745
	v_cmp_eq_u32_e32 vcc, v5, v4
	s_cbranch_vccz .Lxb_nofirst_6
	buffer_wbl2 sc1

; __device__ __forceinline__ unsigned xb_ld(unsigned* p)              { return __hip_atomic_load(p, __ATOMIC_RELAXED, __HIP_MEMORY_SCOPE_AGENT); }
; __device__ __forceinline__ unsigned xb_add(unsigned* p, unsigned v) { return __hip_atomic_fetch_add(p, v, __ATOMIC_RELAXED, __HIP_MEMORY_SCOPE_AGENT); }
; #define XB_SPIN(cond, bar) do { unsigned _sp = 0; while (cond) { \
;     if ((++_sp & 255u) == 0u) { if (xb_ld(&(bar)[XB_TMO])) break; if (_sp > XB_SPIN_CAP) { atomicAdd(&(bar)[XB_TMO], 1u); break; } } } } while (0)
; __device__ __forceinline__ void xcd_barrier(const XcdBarrier& b) {
;     ...
;         unsigned nloc = b.st[0], nx = b.st[1];
;         if (nloc == 0u) { xcd_barrier_complete(bar, b.x, nloc, nx); b.st[0] = nloc; b.st[1] = nx; }
;         const unsigned old = xb_add(&bar[XB_XSUB(b.x)], 1u);
;         const unsigned gen = old / nloc;
;         if (old + 1u == (gen + 1u) * nloc) {
;             __builtin_amdgcn_fence(__ATOMIC_RELEASE, "agent");
;             asm volatile("s_waitcnt vmcnt(0)" ::: "memory");
;             const unsigned og = xb_add(&bar[XB_TOP], 1u);
;             const unsigned tg = og / nx;
;             if (og + 1u == (tg + 1u) * nx) xb_add(&bar[XB_TOPGEN], 1u);
;             else XB_SPIN(xb_ld(&bar[XB_TOPGEN]) == tg, bar);
;             xb_add(&bar[XB_XGEN(b.x)], 1u);
;             __builtin_amdgcn_fence(__ATOMIC_ACQUIRE, "agent");
;             asm volatile("s_waitcnt vmcnt(0)" ::: "memory");
;         } else {
;             XB_SPIN(xb_ld(&bar[XB_XGEN(b.x)]) == gen, bar);
.LBB0_977:
	s_or_b64 exec, exec, s[8:9]
	v_cvt_f32_u32_e32 v4, v2
	s_waitcnt vmcnt(0)
	v_readfirstlane_b32 s6, v3
	v_sub_u32_e32 v3, 0, v2
	v_rcp_iflag_f32_e32 v4, v4
	v_add_u32_e32 v5, s6, v1
	v_mul_f32_e32 v4, 0x4f7ffffe, v4
	v_cvt_u32_f32_e32 v4, v4
	v_mul_lo_u32 v1, v3, v4
	v_mul_hi_u32 v1, v4, v1
	v_add_u32_e32 v1, v4, v1
	v_mul_hi_u32 v1, v5, v1
	v_mul_lo_u32 v3, v1, v2
	v_sub_u32_e32 v3, v5, v3
	v_add_u32_e32 v4, 1, v1
	v_cmp_ge_u32_e32 vcc, v3, v2
	s_nop 1
	v_cndmask_b32_e32 v1, v1, v4, vcc
	v_sub_u32_e32 v4, v3, v2
	v_cndmask_b32_e32 v3, v3, v4, vcc
	v_add_u32_e32 v4, 1, v1
	v_cmp_ge_u32_e32 vcc, v3, v2
	v_add_u32_e32 v3, 1, v5
	s_nop 0
	v_cndmask_b32_e32 v1, v1, v4, vcc
	v_mul_lo_u32 v4, v2, v1
	v_add_u32_e32 v2, v4, v2
	v_cmp_ne_u32_e32 vcc, v3, v2
	s_and_saveexec_b64 s[6:7], vcc
	s_xor_b64 s[6:7], exec, s[6:7]
	s_cbranch_execz .LBB0_991
	v_cmp_eq_u32_e32 vcc, v5, v4
	s_cbranch_vccz .Lxb_nofirst_9
	buffer_wbl2 sc1
.Lxb_nofirst_9:
	s_waitcnt lgkmcnt(0)
	v_mov_b32_e32 v0, 0x2000
	global_load_dword v0, v0, s[4:5] offset:1024 sc1
	s_add_u32 s12, s4, 0x2400
	s_addc_u32 s13, s5, 0
	s_waitcnt vmcnt(0)
	v_cmp_eq_u32_e32 vcc, v0, v1
	s_and_saveexec_b64 s[8:9], vcc
	s_cbranch_execz .LBB0_990
	s_mov_b32 s24, 1
	s_mov_b64 s[14:15], 0
	v_mov_b32_e32 v0, 0
	s_branch .LBB0_981
